# speed-ranked GU tail with a swizzle-slot-preserving mapping (each ranked group takes whole slots), steps 1-2; step 0 static
# speedup vs baseline: 1.0063x; 1.0063x over previous
.LBB0_840:
	s_add_u32 s6, s6, 0xac00000
	s_addc_u32 s7, s7, 0
	v_and_b32_e32 v17, 15, v16
	v_lshrrev_b32_e32 v18, 1, v16
	s_lshl_b32 s2, s2, 5
	v_and_b32_e32 v18, 24, v18
	v_lshlrev_b32_e32 v19, 6, v17
	v_lshlrev_b32_e32 v16, 2, v16
	s_and_b32 s22, s2, 0x60
	s_add_i32 m0, s46, 0x18000
	v_lshl_add_u64 v[8:9], v[8:9], 0, s[70:71]
	v_lshl_or_b32 v19, v18, 1, v19
	v_and_b32_e32 v16, 32, v16
	v_lshl_or_b32 v144, s3, 6, v17
	s_lshl_b32 s3, s3, 13
	s_lshl_b32 s2, s22, 7
	s_waitcnt vmcnt(2)
	s_barrier
	global_load_lds_dwordx4 v[8:9], off
	v_lshl_add_u64 v[6:7], v[6:7], 0, s[70:71]
	s_add_i32 m0, s46, 0x1a000
	s_add_i32 s50, s46, 0x8000
	s_add_i32 s51, s46, 0xa000
	v_bitop3_b32 v145, s2, v19, v16 bitop3:0xf6
	global_load_lds_dwordx4 v[6:7], off
	v_lshl_add_u64 v[2:3], v[2:3], 0, s[70:71]
	s_mov_b32 m0, s50
	s_add_u32 s2, s38, 0x40080
	v_bitop3_b32 v17, v19, s3, v16 bitop3:0xde
	global_load_lds_dwordx4 v[2:3], off
	v_lshl_add_u64 v[2:3], v[4:5], 0, s[70:71]
	s_mov_b32 m0, s51
	s_addc_u32 s3, s39, 0
	global_load_lds_dwordx4 v[2:3], off
	s_add_i32 m0, s46, 0x1c000
	v_lshl_add_u64 v[2:3], s[2:3], 0, v[0:1]
	global_load_lds_dwordx4 v[2:3], off
	v_lshl_add_u64 v[2:3], s[2:3], 0, v[134:135]
	s_add_i32 m0, s46, 0x1e000
	s_cmpk_lt_u32 s9, 0x100
	global_load_lds_dwordx4 v[2:3], off
	v_lshlrev_b32_e32 v2, 14, v10
	v_and_b32_e32 v2, 0xffff8000, v2
	v_lshl_add_u32 v2, v11, 11, v2
	v_and_b32_e32 v3, 1, v10
	v_lshl_or_b32 v2, v3, 6, v2
	v_lshl_add_u32 v136, v12, 1, v2
	v_lshlrev_b32_e32 v2, 14, v13
	v_and_b32_e32 v2, 0xffff8000, v2
	s_waitcnt vmcnt(6)
	v_lshl_add_u32 v2, v14, 11, v2
	v_and_b32_e32 v3, 1, v13
	v_lshl_or_b32 v2, v3, 6, v2
	s_cselect_b64 s[14:15], -1, 0
	v_or_b32_e32 v146, s22, v18
	v_mov_b32_e32 v137, v1
	v_lshl_add_u32 v138, v15, 1, v2
	v_mov_b32_e32 v139, v1
	s_mov_b32 s52, 0
	v_add_u32_e32 v147, 0, v17
	s_barrier
	s_mov_b32 s100, 0x10000
	s_cmp_eq_u32 s65, 0
	s_cbranch_scc1 .Lslot_done
	s_cmpk_lg_u32 s33, 0x100
	s_cbranch_scc1 .Lslot_done
	s_load_dwordx2 s[98:99], s[0:1], 0x128
	s_and_b32 s101, s8, 7
	s_lshl_b32 s101, s101, 8
	s_waitcnt lgkmcnt(0)
	s_add_u32 s98, s98, s101
	s_addc_u32 s99, s99, 0
	s_add_u32 s98, s98, 0x302400
	s_addc_u32 s99, s99, 0
	global_load_dword v2, v1, s[98:99] sc1
	s_waitcnt vmcnt(0)
	v_readfirstlane_b32 s101, v2
	s_nop 3
	s_cmp_lt_u32 s101, 3
	s_cbranch_scc0 .Lslot_done
	s_lshr_b32 s100, s8, 3
	s_cmp_lt_u32 s100, 24
	s_cbranch_scc0 .Lslot_hi
	s_cmp_ge_u32 s100, 12
	s_cselect_b32 s98, 1, 0
	s_cselect_b32 s99, 12, 0
	s_sub_i32 s100, s100, s99
	s_lshl_b32 s101, s101, 1
	s_add_i32 s101, s101, s98
	s_branch .Lslot_fin
.Lslot_hi:
	s_sub_i32 s100, s100, 24
	s_lshl_b32 s101, s101, 3
	s_add_i32 s100, s100, s101
	s_cmp_ge_u32 s100, 12
	s_cselect_b32 s98, 1, 0
	s_cselect_b32 s99, 12, 0
	s_sub_i32 s100, s100, s99
	s_add_i32 s101, s98, 6
.Lslot_fin:
	s_lshl_b32 s100, s100, 3
	s_add_i32 s100, s100, s101
